# prompt-attention softmax: cross-lane row max via v_permlane16/32_swap instead of ds_bpermute (on top of stacked variant)
# speedup vs baseline: 1.0107x; 1.0036x over previous
; #define LAS __attribute__((address_space(3)))
; template <int NKS, int NCT, int NQS, int KSTR>
; DEVI void attn_qk(LAS unsigned char* kbase, const h8 (&qf)[NQS][NKS], f4 (&o)[NQS][NCT], float (&mrow)[NQS], float (&lrow)[NQS], h8 (&pf)[NQS][2], const int nkt, const int lane) {
;     ...
;     for (int kt = 0; kt < 4; ++kt) if (kt < nkt) {
; #pragma unroll
;         for (int qs = 0; qs < NQS; ++qs) s[qs][kt] = (f4){0.f, 0.f, 0.f, 0.f};
; #pragma unroll
;         for (int ks = 0; ks < NKS; ++ks) { const h8 kf = *(const LAS h8*)(kbase + (kt * 16 + fr) * KSTR + ks * 64 + g * 16);
; #pragma unroll
;             for (int qs = 0; qs < NQS; ++qs) s[qs][kt] = __builtin_amdgcn_mfma_f32_16x16x32_f16(kf, qf[qs][ks], s[qs][kt], 0, 0, 0); } }
.LBB0_886:
	s_and_b32 s8, s30, 1
	s_mul_i32 s9, s8, 0x3800
	v_add_u32_e32 v83, s9, v104
	v_add_u32_e32 v96, v83, v105
	v_add_u32_e32 v83, v83, v106
	s_mulk_i32 s8, 0x2800
	ds_read_b128 v[150:153], v96
	ds_read_b128 v[154:157], v96 offset:64
	ds_read_b128 v[158:161], v96 offset:128
	ds_read_b128 v[162:165], v96 offset:3584
	ds_read_b128 v[168:171], v96 offset:3648
	ds_read_b128 v[172:175], v96 offset:3712
	ds_read_b128 v[176:179], v96 offset:7168
	ds_read_b128 v[180:183], v96 offset:7232
	ds_read_b128 v[184:187], v96 offset:7296
	ds_read_b128 v[188:191], v83
	ds_read_b128 v[192:195], v83 offset:64
	ds_read_b128 v[196:199], v83 offset:128
	s_waitcnt lgkmcnt(11)
	v_mfma_f32_16x16x32_f16 v[88:91], v[150:153], v[0:3], 0
	v_mfma_f32_16x16x32_f16 v[108:111], v[150:153], v[12:15], 0
	s_waitcnt lgkmcnt(10)
	v_mfma_f32_16x16x32_f16 v[88:91], v[154:157], v[4:7], v[88:91]
	v_mfma_f32_16x16x32_f16 v[108:111], v[154:157], v[16:19], v[108:111]
	s_waitcnt lgkmcnt(9)
	v_mfma_f32_16x16x32_f16 v[88:91], v[158:161], v[8:11], v[88:91]
	v_mfma_f32_16x16x32_f16 v[108:111], v[158:161], v[20:23], v[108:111]
	s_waitcnt lgkmcnt(8)
	v_mfma_f32_16x16x32_f16 v[92:95], v[162:165], v[0:3], 0
	v_mfma_f32_16x16x32_f16 v[112:115], v[162:165], v[12:15], 0
	s_waitcnt lgkmcnt(7)
	v_mfma_f32_16x16x32_f16 v[92:95], v[168:171], v[4:7], v[92:95]
	v_mfma_f32_16x16x32_f16 v[112:115], v[168:171], v[16:19], v[112:115]
	s_waitcnt lgkmcnt(6)
	v_mfma_f32_16x16x32_f16 v[92:95], v[172:175], v[8:11], v[92:95]
	v_mfma_f32_16x16x32_f16 v[112:115], v[172:175], v[20:23], v[112:115]
	s_waitcnt lgkmcnt(5)
	v_mfma_f32_16x16x32_f16 v[116:119], v[176:179], v[0:3], 0
	v_mfma_f32_16x16x32_f16 v[120:123], v[176:179], v[12:15], 0
	s_waitcnt lgkmcnt(4)
	v_mfma_f32_16x16x32_f16 v[116:119], v[180:183], v[4:7], v[116:119]
	v_mfma_f32_16x16x32_f16 v[120:123], v[180:183], v[16:19], v[120:123]
	s_waitcnt lgkmcnt(3)
	v_mfma_f32_16x16x32_f16 v[116:119], v[184:187], v[8:11], v[116:119]
	v_mfma_f32_16x16x32_f16 v[120:123], v[184:187], v[20:23], v[120:123]
	s_waitcnt lgkmcnt(2)
	v_mfma_f32_16x16x32_f16 v[124:127], v[188:191], v[0:3], 0
	v_mfma_f32_16x16x32_f16 v[128:131], v[188:191], v[12:15], 0
	s_waitcnt lgkmcnt(1)
	v_mfma_f32_16x16x32_f16 v[124:127], v[192:195], v[4:7], v[124:127]
	v_mfma_f32_16x16x32_f16 v[128:131], v[192:195], v[16:19], v[128:131]
	s_waitcnt lgkmcnt(0)
; DEVI float shx(float v, int o, int lane) { return __builtin_bit_cast(float, __builtin_amdgcn_ds_bpermute((lane ^ o) << 2, __builtin_bit_cast(int, v))); }
; template <int NKS, int NCT, int NQS, int KSTR>
; DEVI void attn_qk(LAS unsigned char* kbase, const h8 (&qf)[NQS][NKS], f4 (&o)[NQS][NCT], float (&mrow)[NQS], float (&lrow)[NQS], h8 (&pf)[NQS][2], const int nkt, const int lane) {
;     ...
;             for (int e = 0; e < 4; ++e) mx = fmaxf(mx, s[qs][kt][e]);
;         mx = fmaxf(mx, shx(mx, 16, lane)); mx = fmaxf(mx, shx(mx, 32, lane));
;         const float mnew = fmaxf(mrow[qs], mx), alpha = __builtin_amdgcn_exp2f(mrow[qs] - mnew); mrow[qs] = mnew;
;         float ps = 0.f;
; #pragma unroll
;         for (int kt = 0; kt < 4; ++kt)
; #pragma unroll
;             for (int e = 0; e < 4; ++e) { const float p = __builtin_amdgcn_exp2f(s[qs][kt][e] - mnew); s[qs][kt][e] = p; ps += p; }
;         lrow[qs] = lrow[qs] * alpha + ps;
; #pragma unroll
;         for (int ct = 0; ct < NCT; ++ct) o[qs][ct] *= alpha;
; #pragma unroll
;         for (int k2 = 0; k2 < 2; ++k2) pf[qs][k2] = pack8(s[qs][2 * k2], s[qs][2 * k2 + 1]);
	v_mfma_f32_16x16x32_f16 v[124:127], v[196:199], v[8:11], v[124:127]
	v_mfma_f32_16x16x32_f16 v[128:131], v[196:199], v[20:23], v[128:131]
	s_nop 3
	s_mov_b32 s9, 0xf149f2ca
	v_max3_f32 v83, v88, s9, v89
	v_max3_f32 v83, v83, v90, v91
	v_max3_f32 v83, v83, v92, v93
	v_max3_f32 v83, v83, v94, v95
	v_max3_f32 v83, v83, v116, v117
	v_max3_f32 v83, v83, v118, v119
	v_max3_f32 v83, v83, v124, v125
	v_max3_f32 v83, v83, v126, v127
	v_mov_b32_e32 v252, v83
	v_mov_b32_e32 v84, v83
	s_nop 1
	v_permlane16_swap_b32_e32 v252, v84
	v_max_f32_e32 v83, v252, v84
	v_mov_b32_e32 v252, v83
	v_mov_b32_e32 v84, v83
	s_nop 1
	v_permlane32_swap_b32_e32 v252, v84
	v_max3_f32 v148, v82, v252, v84
	v_sub_f32_e32 v83, v82, v148
	v_sub_f32_e32 v82, v88, v148
	v_exp_f32_e32 v132, v82
	v_sub_f32_e32 v82, v93, v148
	v_exp_f32_e32 v142, v82
	v_sub_f32_e32 v82, v94, v148
	v_exp_f32_e32 v144, v82
	v_sub_f32_e32 v82, v95, v148
	v_exp_f32_e32 v146, v82
	v_sub_f32_e32 v82, v116, v148
	v_exp_f32_e32 v116, v83
	v_max3_f32 v83, v108, s9, v109
	v_sub_f32_e32 v85, v90, v148
	v_max3_f32 v83, v83, v110, v111
	v_sub_f32_e32 v86, v91, v148
	v_exp_f32_e32 v136, v85
	v_sub_f32_e32 v85, v118, v148
	v_max3_f32 v83, v83, v112, v113
	v_exp_f32_e32 v138, v86
	v_exp_f32_e32 v86, v85
	v_sub_f32_e32 v85, v119, v148
	v_max3_f32 v83, v83, v114, v115
	v_exp_f32_e32 v88, v85
	v_sub_f32_e32 v85, v124, v148
	v_max3_f32 v83, v83, v120, v121
	v_exp_f32_e32 v90, v85
	v_sub_f32_e32 v85, v125, v148
	v_max3_f32 v83, v83, v122, v123
	v_sub_f32_e32 v87, v92, v148
	v_exp_f32_e32 v92, v85
	v_sub_f32_e32 v85, v126, v148
	v_max3_f32 v83, v83, v128, v129
	v_exp_f32_e32 v94, v85
	v_sub_f32_e32 v85, v127, v148
	v_max3_f32 v83, v83, v130, v131
	v_exp_f32_e32 v96, v85
	v_sub_f32_e32 v84, v89, v148
	v_exp_f32_e32 v134, v84
	v_exp_f32_e32 v140, v87
	v_exp_f32_e32 v82, v82
	v_mov_b32_e32 v253, v83
	v_mov_b32_e32 v85, v83
	s_nop 1
	v_permlane16_swap_b32_e32 v253, v85
	v_max_f32_e32 v83, v253, v85
	v_mov_b32_e32 v253, v83
	v_mov_b32_e32 v85, v83
	s_nop 1
	v_permlane32_swap_b32_e32 v253, v85
	v_sub_f32_e32 v84, v117, v148
	v_exp_f32_e32 v84, v84
	v_pk_mul_f32 v[56:57], v[56:57], v[116:117] op_sel_hi:[1,0]
	v_pk_mul_f32 v[54:55], v[54:55], v[116:117] op_sel_hi:[1,0]
	v_add_u32_e32 v250, s8, v107
	ds_read_b64_tr_b16 v[200:201], v250 offset:28672
	ds_read_b64_tr_b16 v[202:203], v250 offset:31232
	ds_read_b64_tr_b16 v[204:205], v250 offset:28704
	ds_read_b64_tr_b16 v[206:207], v250 offset:31264
	ds_read_b64_tr_b16 v[212:213], v250 offset:28736
	ds_read_b64_tr_b16 v[214:215], v250 offset:31296
	ds_read_b64_tr_b16 v[216:217], v250 offset:28768
	ds_read_b64_tr_b16 v[218:219], v250 offset:31328
	ds_read_b64_tr_b16 v[232:233], v250 offset:33792
	ds_read_b64_tr_b16 v[234:235], v250 offset:36352
	ds_read_b64_tr_b16 v[236:237], v250 offset:33824
	ds_read_b64_tr_b16 v[238:239], v250 offset:36384
	ds_read_b64_tr_b16 v[240:241], v250 offset:33856
	ds_read_b64_tr_b16 v[242:243], v250 offset:36416
	ds_read_b64_tr_b16 v[246:247], v250 offset:33888
	ds_read_b64_tr_b16 v[248:249], v250 offset:36448
	v_max3_f32 v124, v48, v253, v85
	v_sub_f32_e32 v83, v108, v124
	v_exp_f32_e32 v133, v83
	v_sub_f32_e32 v83, v109, v124
	v_exp_f32_e32 v135, v83
	v_sub_f32_e32 v83, v110, v124
	v_exp_f32_e32 v137, v83
	v_sub_f32_e32 v83, v111, v124
	v_exp_f32_e32 v139, v83
	v_sub_f32_e32 v83, v112, v124
	v_exp_f32_e32 v141, v83
	v_sub_f32_e32 v83, v113, v124
	v_pk_add_f32 v[108:109], v[132:133], 0 op_sel_hi:[1,0]
	v_exp_f32_e32 v143, v83
	v_pk_add_f32 v[108:109], v[134:135], v[108:109]
	v_sub_f32_e32 v83, v114, v124
	v_pk_add_f32 v[108:109], v[136:137], v[108:109]
	v_exp_f32_e32 v145, v83
	v_sub_f32_e32 v83, v115, v124
	v_pk_add_f32 v[108:109], v[138:139], v[108:109]
	v_exp_f32_e32 v147, v83
	v_sub_f32_e32 v83, v120, v124
	v_pk_add_f32 v[108:109], v[140:141], v[108:109]
	v_exp_f32_e32 v83, v83
	v_sub_f32_e32 v85, v121, v124
	v_pk_add_f32 v[108:109], v[142:143], v[108:109]
	v_exp_f32_e32 v85, v85
	v_sub_f32_e32 v87, v122, v124
	v_exp_f32_e32 v87, v87
	v_sub_f32_e32 v89, v123, v124
	v_pk_add_f32 v[108:109], v[144:145], v[108:109]
	v_exp_f32_e32 v89, v89
	v_sub_f32_e32 v91, v128, v124
	v_pk_add_f32 v[108:109], v[146:147], v[108:109]
	v_exp_f32_e32 v91, v91
	v_sub_f32_e32 v93, v129, v124
	v_pk_add_f32 v[108:109], v[82:83], v[108:109]
	v_exp_f32_e32 v93, v93
	v_sub_f32_e32 v95, v130, v124
	v_pk_add_f32 v[108:109], v[84:85], v[108:109]
	v_sub_f32_e32 v48, v48, v124
	v_exp_f32_e32 v95, v95
	v_sub_f32_e32 v97, v131, v124
	v_pk_add_f32 v[108:109], v[86:87], v[108:109]
	v_pk_mul_f32 v[60:61], v[60:61], v[116:117] op_sel_hi:[1,0]
	v_pk_mul_f32 v[58:59], v[58:59], v[116:117] op_sel_hi:[1,0]
	v_pk_mul_f32 v[64:65], v[64:65], v[116:117] op_sel_hi:[1,0]
	v_pk_mul_f32 v[62:63], v[62:63], v[116:117] op_sel_hi:[1,0]
	v_pk_mul_f32 v[68:69], v[68:69], v[116:117] op_sel_hi:[1,0]
	v_pk_mul_f32 v[66:67], v[66:67], v[116:117] op_sel_hi:[1,0]
	v_exp_f32_e32 v97, v97
	v_exp_f32_e32 v117, v48
	v_pk_add_f32 v[108:109], v[88:89], v[108:109]
	v_mov_b32_e32 v48, v117
	v_pk_add_f32 v[108:109], v[90:91], v[108:109]
	v_pk_mul_f32 v[30:31], v[30:31], v[48:49] op_sel_hi:[1,0]
	v_pk_add_f32 v[108:109], v[92:93], v[108:109]
	v_pk_mul_f32 v[28:29], v[28:29], v[48:49] op_sel_hi:[1,0]
	v_pk_add_f32 v[108:109], v[94:95], v[108:109]
	v_pk_mul_f32 v[34:35], v[34:35], v[48:49] op_sel_hi:[1,0]
	v_pk_add_f32 v[108:109], v[96:97], v[108:109]
	v_pk_mul_f32 v[32:33], v[32:33], v[48:49] op_sel_hi:[1,0]
	v_pk_fma_f32 v[74:75], v[74:75], v[116:117], v[108:109]
	v_pk_mul_f32 v[42:43], v[42:43], v[48:49] op_sel_hi:[1,0]
	v_pk_mul_f32 v[40:41], v[40:41], v[48:49] op_sel_hi:[1,0]
	v_pk_mul_f32 v[46:47], v[48:49], v[46:47] op_sel_hi:[0,1]
	v_pk_mul_f32 v[44:45], v[48:49], v[44:45] op_sel_hi:[0,1]
	s_andn2_b64 vcc, exec, s[0:1]
	s_cbranch_vccnz .Lpa_nostore
	s_and_b32 s100, s29, 1
	s_mul_i32 s101, s100, 0x3800
	s_add_i32 s101, s101, 16
	v_add_u32_e32 v251, s101, v101
	v_add_u32_e32 v252, s101, v102
	s_mulk_i32 s100, 0x2800
	v_add_u32_e32 v253, s100, v103
	s_waitcnt vmcnt(1)
	ds_write_b128 v251, v[24:27]
	s_and_saveexec_b64 s[100:101], s[6:7]
	ds_write_b128 v252, v[36:39]
	s_or_b64 exec, exec, s[100:101]
	s_waitcnt vmcnt(0)
	ds_write_b128 v253, v[50:53] offset:28672
